# final RMSNorm rows XCD-local, last seam uses the XCD-local barrier
# speedup vs baseline: 1.0085x; 1.0007x over previous
; __device__ __forceinline__ void xcd_barrier(const XcdBarrier& b) {
;     asm volatile("s_waitcnt vmcnt(0)" ::: "memory");
;     __syncthreads();
;     if (threadIdx.x == 0) {
;         unsigned* bar = b.bar;
;         __builtin_amdgcn_s_waitcnt(0);
;         unsigned nloc = b.st[0], nx = b.st[1];
;         if (nloc == 0u) { xcd_barrier_complete(bar, b.x, nloc, nx); b.st[0] = nloc; b.st[1] = nx; }
.Lxl_chk_done:
	s_cmp_lg_u32 s97, 1
	s_cbranch_scc1 .Lxl_flag_done
	s_nop 4
	global_load_dword v20, v193, s[6:7] offset:4 sc1
	s_waitcnt vmcnt(0)
	v_readfirstlane_b32 s2, v20
	s_nop 3
	s_cmp_eq_u32 s2, 0
	s_cselect_b32 s101, 1, 0
	v_mov_b32_e32 v20, s101
	v_mov_b32_e32 v21, 0x23ff0
	ds_write_b32 v21, v20

; __device__ __forceinline__ unsigned xb_ld(unsigned* p)              { return __hip_atomic_load(p, __ATOMIC_RELAXED, __HIP_MEMORY_SCOPE_AGENT); }
; __device__ __forceinline__ unsigned xb_add(unsigned* p, unsigned v) { return __hip_atomic_fetch_add(p, v, __ATOMIC_RELAXED, __HIP_MEMORY_SCOPE_AGENT); }
; #define XB_SPIN(cond, bar) do { unsigned _sp = 0; while (cond) { __builtin_amdgcn_s_sleep(1); \
;     if ((++_sp & 255u) == 0u) { if (xb_ld(&(bar)[XB_TMO])) break; if (_sp > XB_SPIN_CAP) { atomicAdd(&(bar)[XB_TMO], 1u); break; } } } } while (0)
; __device__ __forceinline__ void xcd_barrier(const XcdBarrier& b) {
;     ...
;         const unsigned old = xb_add(&bar[XB_XSUB(b.x)], 1u);
;         const unsigned gen = old / nloc;
;         if (old + 1u == (gen + 1u) * nloc) {
;             __builtin_amdgcn_fence(__ATOMIC_RELEASE, "agent");
;             asm volatile("s_waitcnt vmcnt(0)" ::: "memory");
;             const unsigned og = xb_add(&bar[XB_TOP], 1u);
;             const unsigned tg = og / nx;
;             if (og + 1u == (tg + 1u) * nx) xb_add(&bar[XB_TOPGEN], 1u);
;             else XB_SPIN(xb_ld(&bar[XB_TOPGEN]) == tg, bar);
.LBB0_394:
	s_andn2_saveexec_b64 s[6:7], s[6:7]
	s_cbranch_execz .LBB0_9
	s_mov_b64 s[6:7], exec
	s_waitcnt lgkmcnt(0)
	s_cmp_eq_u32 s101, 0
	s_cbranch_scc1 .Lxl_global
	s_cmp_lt_i32 s97, 1
	s_cbranch_scc1 .Lxl_global
	s_mul_i32 s2, s97, 0xcd
	s_lshr_b32 s2, s2, 10
	s_mul_i32 s2, s2, 5
	s_sub_i32 s2, s97, s2
	s_cmp_eq_u32 s2, 1
	s_cbranch_scc1 .Lxl_release
	s_cmp_eq_u32 s2, 4
	s_cbranch_scc1 .Lxl_release

; #define INP(k) ldptr(PT, (k))
; __global__ void __launch_bounds__(NTHR, 2) hybrid_fwd(Args args) {
;     ...
;     { const float* nfin = INP(13); const bf16* XBf = (const bf16*)(ws + WS_XB);
;       for (int m = gw; m < S; m += NGW) { const __attribute__((address_space(1))) v2u* xr = (const __attribute__((address_space(1))) v2u*)(XBf + (size_t)m * DM) + lane; f32x4 v[4]; float ss = 0.f;
.LBB0_413:
	v_mov_b32_e32 v0, 0x23ff0
	ds_read_b32 v0, v0
	s_movk_i32 s100, 0x3fff
	s_waitcnt lgkmcnt(0)
	v_readfirstlane_b32 s0, v0
	s_nop 3
	s_cmp_eq_u32 s0, 0
	s_cbranch_scc1 .Lfin_noremap
	s_and_b32 s0, s27, 7
	s_lshl_b32 s0, s0, 11
	s_lshr_b32 s1, s27, 3
	s_lshl_b32 s1, s1, 6
	s_add_i32 s84, s0, s1
	s_add_i32 s84, s84, s3
	s_add_i32 s100, s84, 56
	s_mov_b32 s94, 8
	s_mov_b64 s[30:31], 0x4000
	s_mov_b64 s[34:35], 0x8000

; __device__ __forceinline__ float bflo(unsigned u) { return __uint_as_float(u << 16); }
; __device__ __forceinline__ float bfhi(unsigned u) { return __uint_as_float(u & 0xffff0000u); }
; __global__ void __launch_bounds__(NTHR, 2) hybrid_fwd(Args args) {
;     ...
;       for (int m = gw; m < S; m += NGW) { const __attribute__((address_space(1))) v2u* xr = (const __attribute__((address_space(1))) v2u*)(XBf + (size_t)m * DM) + lane; f32x4 v[4]; float ss = 0.f;
; #pragma unroll
;         for (int j = 0; j < 4; ++j) { const v2u u = xr[64 * j]; v[j] = (f32x4){bflo(u.x), bfhi(u.x), bflo(u.y), bfhi(u.y)}; ss += (v[j][0] * v[j][0] + v[j][1] * v[j][1]) + (v[j][2] * v[j][2] + v[j][3] * v[j][3]); }
;         const float rs = __builtin_amdgcn_rsqf(wave_sum(ss) * (1.0f / 1024.0f) + EPS);
;         __attribute__((address_space(1))) f32x4* orow = (__attribute__((address_space(1))) f32x4*)(xo + (size_t)m * DM) + lane;
; #pragma unroll
;         for (int j = 0; j < 4; ++j) { const f32x4 g = *((const __attribute__((address_space(1))) f32x4*)nfin + lane + 64 * j); __builtin_nontemporal_store(v[j] * rs * g, orow + 64 * j); } } }
.LBB0_415:
	v_mov_b32_e32 v12, v60
	v_mov_b32_e32 v13, v61
	v_mov_b32_e32 v14, v62
	v_mov_b32_e32 v15, v63
	v_mov_b32_e32 v16, v64
	v_mov_b32_e32 v17, v65
	v_mov_b32_e32 v18, v66
	v_mov_b32_e32 v19, v67
	s_add_i32 s84, s84, s94
	v_lshl_add_u64 v[2:3], v[2:3], 0, s[30:31]
	s_cmp_gt_i32 s84, s100
	s_cbranch_scc1 .Lfin_nopf
	global_load_dwordx2 v[60:61], v[2:3], off offset:-1536
	global_load_dwordx2 v[62:63], v[2:3], off offset:-1024
	global_load_dwordx2 v[64:65], v[2:3], off offset:-512
	global_load_dwordx2 v[66:67], v[2:3], off
.Lfin_nopf:
	v_lshlrev_b32_e32 v20, 16, v12
	v_and_b32_e32 v21, 0xffff0000, v12
	v_lshlrev_b32_e32 v12, 16, v13
	v_and_b32_e32 v13, 0xffff0000, v13
	v_lshlrev_b32_e32 v23, 16, v15
	v_lshlrev_b32_e32 v22, 16, v14
	v_and_b32_e32 v15, 0xffff0000, v15
	v_and_b32_e32 v14, 0xffff0000, v14
	v_and_b32_e32 v25, 0xffff0000, v16
	v_lshlrev_b32_e32 v27, 16, v18
	v_and_b32_e32 v29, 0xffff0000, v18
	v_mul_f32_e32 v26, v13, v13
	v_mul_f32_e32 v28, v21, v21
	v_lshlrev_b32_e32 v24, 16, v16
	v_lshlrev_b32_e32 v16, 16, v17
	v_and_b32_e32 v17, 0xffff0000, v17
	v_pk_mul_f32 v[30:31], v[14:15], v[14:15]
	v_mov_b32_e32 v33, v27
	v_mul_f32_e32 v32, v25, v25
	v_pk_fma_f32 v[36:37], v[12:13], v[12:13], v[26:27] op_sel_hi:[1,1,0]
	v_pk_fma_f32 v[38:39], v[20:21], v[20:21], v[28:29] op_sel_hi:[1,1,0]
	v_lshlrev_b32_e32 v18, 16, v19
	v_and_b32_e32 v19, 0xffff0000, v19
	v_mul_f32_e32 v34, v17, v17
	v_pk_fma_f32 v[30:31], v[22:23], v[22:23], v[30:31]
	v_pk_fma_f32 v[40:41], v[24:25], v[24:25], v[32:33] op_sel_hi:[1,1,0]
	v_mov_b32_e32 v26, v38
	v_mov_b32_e32 v32, v36
	v_mul_f32_e32 v7, v29, v29
	v_mul_f32_e32 v42, v18, v18
	v_mul_f32_e32 v43, v19, v19
	v_pk_fma_f32 v[34:35], v[16:17], v[16:17], v[34:35] op_sel_hi:[1,1,0]
	v_pk_add_f32 v[36:37], v[38:39], v[36:37]
	v_pk_add_f32 v[30:31], v[30:31], v[30:31] op_sel:[0,1] op_sel_hi:[1,0]
	v_pk_mul_f32 v[32:33], v[26:27], v[32:33]
	v_mov_b32_e32 v41, v42
	v_mov_b32_e32 v35, v43
	v_mov_b32_e32 v31, v7
	v_mov_b32_e32 v37, v33
	v_pk_add_f32 v[34:35], v[40:41], v[34:35]
	v_pk_add_f32 v[30:31], v[36:37], v[30:31]
	v_mov_b32_e32 v28, v27
	v_pk_add_f32 v[30:31], v[30:31], v[34:35]
	s_nop 0
	v_add_f32_e32 v7, v30, v31
	s_nop 1
	v_add_f32_dpp v7, v7, v7 quad_perm:[1,0,3,2] row_mask:0xf bank_mask:0xf bound_ctrl:1
	s_nop 1
	v_add_f32_dpp v7, v7, v7 quad_perm:[2,3,0,1] row_mask:0xf bank_mask:0xf bound_ctrl:1
	s_nop 1
	v_add_f32_dpp v7, v7, v7 row_half_mirror row_mask:0xf bank_mask:0xf bound_ctrl:1
	s_nop 1
	v_add_f32_dpp v7, v7, v7 row_mirror row_mask:0xf bank_mask:0xf bound_ctrl:1
	s_nop 0
	v_readlane_b32 s2, v7, 16
	v_readlane_b32 s3, v7, 48
	v_readlane_b32 s0, v7, 0
	v_readlane_b32 s1, v7, 32
	v_mov_b32_e32 v30, s2
	v_mov_b32_e32 v31, s3
	v_pk_add_f32 v[30:31], s[0:1], v[30:31]
	s_nop 0
	v_add_f32_e32 v7, v30, v31
	v_fmamk_f32 v7, v7, 0x3a800000, v6
	v_rsq_f32_e32 v26, v7
	s_nop 0
	v_pk_mul_f32 v[20:21], v[26:27], v[20:21] op_sel_hi:[0,1]
	v_pk_mul_f32 v[12:13], v[26:27], v[12:13] op_sel_hi:[0,1]
	v_pk_mul_f32 v[10:11], v[12:13], v[46:47]
	v_pk_mul_f32 v[8:9], v[20:21], v[44:45]
	global_store_dwordx4 v[4:5], v[8:11], off offset:-2048 nt
	v_mov_b32_e32 v12, v23
	v_mov_b32_e32 v13, v15
	v_mov_b32_e32 v23, v14
	v_pk_mul_f32 v[12:13], v[26:27], v[12:13] op_sel_hi:[0,1]
	v_pk_mul_f32 v[14:15], v[26:27], v[22:23] op_sel_hi:[0,1]
	v_pk_mul_f32 v[68:69], v[14:15], v[48:49]
	v_pk_mul_f32 v[70:71], v[12:13], v[50:51]
	global_store_dwordx4 v[4:5], v[68:71], off offset:-1024 nt
	v_pk_mul_f32 v[12:13], v[26:27], v[16:17] op_sel_hi:[0,1]
	v_pk_mul_f32 v[14:15], v[26:27], v[24:25] op_sel_hi:[0,1]
	v_pk_mul_f32 v[72:73], v[14:15], v[52:53]
	v_pk_mul_f32 v[74:75], v[12:13], v[54:55]
	global_store_dwordx4 v[4:5], v[72:75], off nt
	v_pk_mul_f32 v[12:13], v[26:27], v[18:19] op_sel_hi:[0,1]
	v_pk_mul_f32 v[14:15], v[26:27], v[28:29] op_sel_hi:[0,1]
	v_pk_mul_f32 v[76:77], v[14:15], v[56:57]
	v_pk_mul_f32 v[78:79], v[12:13], v[58:59]
	global_store_dwordx4 v[4:5], v[76:79], off offset:1024 nt
	v_lshl_add_u64 v[4:5], v[4:5], 0, s[34:35]
	s_waitcnt vmcnt(4)
	s_cmp_gt_i32 s84, s100
	s_cbranch_scc0 .LBB0_415
